# attention unit epilogue: LDS-staged transpose, 4 dwordx4 full-row stores instead of 32 short stores per lane; dropped end-of-unit vmcnt(0)
# baseline (speedup 1.0000x reference)
.LBB0_694:
	s_or_b64 exec, exec, s[0:1]
	s_waitcnt lgkmcnt(0)
	v_add_u32_e32 v70, v163, v188
	ds_read_b128 v[32:35], v70 offset:49152
	ds_read_b128 v[36:39], v70 offset:49184
	ds_read_b128 v[40:43], v70 offset:49216
	ds_read_b128 v[44:47], v70 offset:49248
	s_lshl_b32 s0, s91, 11
	s_add_u32 s0, s89, s0
	s_addc_u32 s1, s90, 0
	v_lshlrev_b32_e32 v71, 4, v151
	v_lshl_add_u32 v71, v163, 4, v71
	v_add_u32_e32 v71, 0x12000, v71
	v_lshlrev_b32_e32 v72, 1, v149
	v_lshl_add_u32 v72, v162, 9, v72
	v_lshl_add_u32 v72, v163, 4, v72
	v_add_u32_e32 v72, 0x12000, v72
	v_lshrrev_b32_e32 v73, 3, v151
	v_add_u32_e32 v73, v73, v154
	v_lshlrev_b32_e32 v73, 11, v73
	v_and_b32_e32 v77, 7, v151
	v_lshl_add_u32 v73, v77, 4, v73
	v_add_u32_e32 v74, 0x4000, v73
	v_add_u32_e32 v75, 0x8000, v73
	v_add_u32_e32 v76, 0xc000, v73
	s_waitcnt lgkmcnt(0)
	v_rcp_f32_e32 v32, v32
	v_rcp_f32_e32 v33, v33
	v_rcp_f32_e32 v34, v34
	v_rcp_f32_e32 v35, v35
	v_rcp_f32_e32 v36, v36
	v_rcp_f32_e32 v37, v37
	v_rcp_f32_e32 v38, v38
	v_rcp_f32_e32 v39, v39
	v_rcp_f32_e32 v40, v40
	v_rcp_f32_e32 v41, v41
	v_rcp_f32_e32 v42, v42
	v_rcp_f32_e32 v43, v43
	v_rcp_f32_e32 v44, v44
	v_rcp_f32_e32 v45, v45
	v_rcp_f32_e32 v46, v46
	v_rcp_f32_e32 v47, v47
	v_pk_mul_f32 v[16:17], v[16:17], v[32:33]
	v_pk_mul_f32 v[18:19], v[18:19], v[34:35]
	v_pk_mul_f32 v[20:21], v[20:21], v[36:37]
	v_pk_mul_f32 v[22:23], v[22:23], v[38:39]
	v_pk_mul_f32 v[24:25], v[24:25], v[40:41]
	v_pk_mul_f32 v[26:27], v[26:27], v[42:43]
	v_pk_mul_f32 v[28:29], v[28:29], v[44:45]
	v_pk_mul_f32 v[30:31], v[30:31], v[46:47]
	v_pk_mul_f32 v[0:1], v[0:1], v[32:33]
	v_pk_mul_f32 v[2:3], v[2:3], v[34:35]
	v_pk_mul_f32 v[4:5], v[4:5], v[36:37]
	v_pk_mul_f32 v[6:7], v[6:7], v[38:39]
	v_pk_mul_f32 v[8:9], v[8:9], v[40:41]
	v_pk_mul_f32 v[10:11], v[10:11], v[42:43]
	v_pk_mul_f32 v[12:13], v[12:13], v[44:45]
	v_pk_mul_f32 v[14:15], v[14:15], v[46:47]
	v_cvt_pk_bf16_f32 v48, v16, v17
	v_cvt_pk_bf16_f32 v49, v18, v19
	v_cvt_pk_bf16_f32 v50, v20, v21
	v_cvt_pk_bf16_f32 v51, v22, v23
	v_cvt_pk_bf16_f32 v52, v24, v25
	v_cvt_pk_bf16_f32 v53, v26, v27
	v_cvt_pk_bf16_f32 v54, v28, v29
	v_cvt_pk_bf16_f32 v55, v30, v31
	v_cvt_pk_bf16_f32 v56, v0, v1
	v_cvt_pk_bf16_f32 v57, v2, v3
	v_cvt_pk_bf16_f32 v58, v4, v5
	v_cvt_pk_bf16_f32 v59, v6, v7
	v_cvt_pk_bf16_f32 v60, v8, v9
	v_cvt_pk_bf16_f32 v61, v10, v11
	v_cvt_pk_bf16_f32 v62, v12, v13
	v_cvt_pk_bf16_f32 v63, v14, v15
	ds_write_b16 v72, v48 offset:0
	ds_write_b16_d16_hi v72, v48 offset:128
	ds_write_b16 v72, v49 offset:256
	ds_write_b16_d16_hi v72, v49 offset:384
	ds_write_b16 v72, v50 offset:1024
	ds_write_b16_d16_hi v72, v50 offset:1152
	ds_write_b16 v72, v51 offset:1280
	ds_write_b16_d16_hi v72, v51 offset:1408
	ds_write_b16 v72, v52 offset:2048
	ds_write_b16_d16_hi v72, v52 offset:2176
	ds_write_b16 v72, v53 offset:2304
	ds_write_b16_d16_hi v72, v53 offset:2432
	ds_write_b16 v72, v54 offset:3072
	ds_write_b16_d16_hi v72, v54 offset:3200
	ds_write_b16 v72, v55 offset:3328
	ds_write_b16_d16_hi v72, v55 offset:3456
	ds_write_b16 v72, v56 offset:64
	ds_write_b16_d16_hi v72, v56 offset:192
	ds_write_b16 v72, v57 offset:320
	ds_write_b16_d16_hi v72, v57 offset:448
	ds_write_b16 v72, v58 offset:1088
	ds_write_b16_d16_hi v72, v58 offset:1216
	ds_write_b16 v72, v59 offset:1344
	ds_write_b16_d16_hi v72, v59 offset:1472
	ds_write_b16 v72, v60 offset:2112
	ds_write_b16_d16_hi v72, v60 offset:2240
	ds_write_b16 v72, v61 offset:2368
	ds_write_b16_d16_hi v72, v61 offset:2496
	ds_write_b16 v72, v62 offset:3136
	ds_write_b16_d16_hi v72, v62 offset:3264
	ds_write_b16 v72, v63 offset:3392
	ds_write_b16_d16_hi v72, v63 offset:3520
	s_waitcnt lgkmcnt(0)
	ds_read_b128 v[80:83], v71 offset:0
	ds_read_b128 v[84:87], v71 offset:1024
	ds_read_b128 v[88:91], v71 offset:2048
	ds_read_b128 v[92:95], v71 offset:3072
	s_waitcnt lgkmcnt(3)
	global_store_dwordx4 v73, v[80:83], s[0:1]
	s_waitcnt lgkmcnt(2)
	global_store_dwordx4 v74, v[84:87], s[0:1]
	s_waitcnt lgkmcnt(1)
	global_store_dwordx4 v75, v[88:91], s[0:1]
	s_waitcnt lgkmcnt(0)
	global_store_dwordx4 v76, v[92:95], s[0:1]
	s_mov_b64 s[0:1], 0
	s_and_b64 vcc, exec, s[58:59]
	s_barrier
	s_cbranch_vccnz .LBB0_692
